# ml_pass2 epilogue: O-gate bf16 unpack moved after the final wait, early vmcnt wait before the transpose barrier dropped
# speedup vs baseline: 1.0150x; 1.0017x over previous
.LBB0_197:
	s_or_b64 exec, exec, s[0:1]
	s_add_i32 s0, 16, 0x23a00
	s_waitcnt vmcnt(15)
	v_lshl_add_u32 v10, v95, 4, s0
	s_waitcnt lgkmcnt(0)
	s_barrier
	ds_read_b128 v[136:139], v10
	ds_read_b128 v[140:143], v10 offset:64
	ds_read_b128 v[144:147], v10 offset:128
	ds_read_b128 v[148:151], v10 offset:192
	v_lshlrev_b32_e32 v8, 2, v96
	s_waitcnt vmcnt(14)
	v_mul_u32_u24_e32 v13, 0x410, v95
	v_add_u32_e32 v9, 16, v8
	v_add_lshl_u32 v13, v13, s17, 2
	s_waitcnt lgkmcnt(0)
	v_mul_f32_e32 v12, v24, v136
	v_add_u32_e32 v14, v9, v13
	ds_write_b32 v14, v12 offset:17408
	v_mul_f32_e32 v11, v28, v136
	v_add3_u32 v12, 16, v13, v8
	ds_write_b32 v12, v11 offset:17472
	v_lshl_or_b32 v11, v95, 2, 1
	v_lshl_add_u32 v12, v11, 2, s0
	v_mul_u32_u24_e32 v11, 0x104, v11
	v_add_lshl_u32 v11, v11, s17, 2
	v_add_u32_e32 v9, v9, v11
	v_add3_u32 v8, 16, v11, v8
	v_mul_f32_e32 v13, v25, v137
	ds_write_b32 v9, v13 offset:17408
	v_mul_f32_e32 v9, v29, v137
	ds_write_b32 v8, v9 offset:17472
	v_add_u32_e32 v13, 0x4800, v8
	v_add_u32_e32 v14, 0x4c00, v8
	v_add_u32_e32 v15, 0x8000, v8
	v_add_u32_e32 v12, 0x410, v8
	v_mul_f32_e32 v11, v26, v138
	v_mul_f32_e32 v9, v30, v138
	ds_write2_b32 v13, v11, v9 offset0:4 offset1:20
	v_add_u32_e32 v13, 0x820, v8
	s_movk_i32 s0, 0x410
	v_readlane_b32 s84, v254, 20
	v_readlane_b32 s86, v254, 22
	v_mul_f32_e32 v11, v27, v139
	v_mul_f32_e32 v9, v31, v139
	ds_write2_b32 v14, v11, v9 offset0:8 offset1:24
	v_add_u32_e32 v14, 0x3cf0, v8
	v_readlane_b32 s87, v254, 23
	s_nop 0
	v_mul_f32_e32 v11, v36, v140
	v_mul_f32_e32 v9, v48, v140
	ds_write2_b32 v15, v11, v9 offset0:60 offset1:76
	v_add_u32_e32 v15, 0x8400, v8
	v_mul_f32_e32 v11, v37, v141
	v_mul_f32_e32 v9, v49, v141
	ds_write2_b32 v15, v11, v9 offset0:64 offset1:80
	v_add_u32_e32 v15, 0x8800, v8
	v_readlane_b32 s85, v254, 21
	v_readlane_b32 s88, v254, 24
	v_mul_f32_e32 v11, v38, v142
	v_mul_f32_e32 v9, v50, v142
	ds_write2_b32 v15, v11, v9 offset0:68 offset1:84
	v_add_u32_e32 v15, 0x8c00, v8
	v_readlane_b32 s89, v254, 25
	v_readlane_b32 s90, v254, 26
	v_readlane_b32 s91, v254, 27
	v_mul_f32_e32 v11, v39, v143
	v_mul_f32_e32 v9, v51, v143
	ds_write2_b32 v15, v11, v9 offset0:72 offset1:88
	v_add_u32_e32 v15, 0xc000, v8
	v_readlane_b32 s92, v254, 28
	v_readlane_b32 s93, v254, 29
	v_readlane_b32 s94, v254, 30
	v_mul_f32_e32 v11, v32, v144
	v_mul_f32_e32 v9, v40, v144
	ds_write2_b32 v15, v11, v9 offset0:124 offset1:140
	v_add_u32_e32 v15, 0xc400, v8
	v_readlane_b32 s95, v254, 31
	v_readlane_b32 s96, v254, 32
	v_readlane_b32 s97, v254, 33
	v_mul_f32_e32 v11, v33, v145
	v_mul_f32_e32 v9, v41, v145
	ds_write2_b32 v15, v11, v9 offset0:128 offset1:144
	v_add_u32_e32 v15, 0xc800, v8
	v_add_u32_e32 v8, 0xcc00, v8
	v_readlane_b32 s98, v254, 34
	v_readlane_b32 s99, v254, 35
	v_mul_f32_e32 v11, v34, v146
	v_mul_f32_e32 v9, v42, v146
	ds_write2_b32 v15, v11, v9 offset0:132 offset1:148
	v_mul_f32_e32 v11, v35, v147
	v_mul_f32_e32 v9, v43, v147
	ds_write2_b32 v8, v11, v9 offset0:136 offset1:152
	v_add_u32_e32 v11, 0xfc00, v12
	v_mul_f32_e32 v9, v44, v148
	v_mul_f32_e32 v8, v52, v148
	ds_write2_b32 v11, v9, v8 offset0:184 offset1:200
	v_add_u32_e32 v11, 0xfc00, v13
	v_mul_f32_e32 v9, v45, v149
	v_mul_f32_e32 v8, v53, v149
	ds_write2_b32 v11, v9, v8 offset0:184 offset1:200
	v_add_u32_e32 v11, 0xcc00, v14
	v_lshlrev_b32_e32 v53, 2, v62
	v_mul_f32_e32 v9, v46, v150
	v_mul_f32_e32 v8, v54, v150
	ds_write2_b32 v11, v9, v8 offset0:136 offset1:152
	v_add_u32_e32 v10, 0xd000, v14
	v_mul_f32_e32 v9, v47, v151
	v_mul_f32_e32 v8, v55, v151
	ds_write2_b32 v10, v9, v8 offset0:140 offset1:156
	v_mul_lo_u32 v8, v94, s0
	v_lshlrev_b32_e32 v9, 2, v104
	v_add3_u32 v10, 16, v8, v9
	s_waitcnt lgkmcnt(0)
	s_barrier
	ds_read_b128 v[40:43], v10 offset:17408
	ds_read_b128 v[36:39], v10 offset:17424
	ds_read_b128 v[32:35], v10 offset:17664
	ds_read_b128 v[28:31], v10 offset:17680
	ds_read_b128 v[24:27], v10 offset:17920
	ds_read_b128 v[20:23], v10 offset:17936
	ds_read_b128 v[12:15], v10 offset:18176
	s_waitcnt lgkmcnt(6)
	v_mul_f32_e32 v11, v41, v41
	v_fmac_f32_e32 v11, v40, v40
	v_fmac_f32_e32 v11, v42, v42
	v_fmac_f32_e32 v11, v43, v43
	s_waitcnt lgkmcnt(5)
	v_fmac_f32_e32 v11, v36, v36
	v_fmac_f32_e32 v11, v37, v37
	v_fmac_f32_e32 v11, v38, v38
	v_fmac_f32_e32 v11, v39, v39
	s_waitcnt lgkmcnt(4)
	v_fmac_f32_e32 v11, v32, v32
	v_fmac_f32_e32 v11, v33, v33
	v_fmac_f32_e32 v11, v34, v34
	v_fmac_f32_e32 v11, v35, v35
	s_waitcnt lgkmcnt(3)
	v_fmac_f32_e32 v11, v28, v28
	v_fmac_f32_e32 v11, v29, v29
	v_fmac_f32_e32 v11, v30, v30
	v_fmac_f32_e32 v11, v31, v31
	s_waitcnt lgkmcnt(2)
	v_fmac_f32_e32 v11, v24, v24
	v_fmac_f32_e32 v11, v25, v25
	v_fmac_f32_e32 v11, v26, v26
	v_fmac_f32_e32 v11, v27, v27
	s_waitcnt lgkmcnt(1)
	v_fmac_f32_e32 v11, v20, v20
	v_fmac_f32_e32 v11, v21, v21
	v_fmac_f32_e32 v11, v22, v22
	v_fmac_f32_e32 v11, v23, v23
	s_waitcnt lgkmcnt(0)
	v_pk_mul_f32 v[8:9], v[12:13], v[12:13]
	v_add_f32_e32 v8, v11, v8
	v_add_f32_e32 v11, v8, v9
	v_pk_mul_f32 v[8:9], v[14:15], v[14:15]
	v_readlane_b32 s0, v251, 57
	v_add_f32_e32 v8, v11, v8
	v_add_f32_e32 v46, v8, v9
	ds_read_b128 v[8:11], v10 offset:18192
	v_readlane_b32 s1, v251, 58
	s_waitcnt lgkmcnt(0)
	v_pk_mul_f32 v[44:45], v[8:9], v[8:9]
	s_nop 0
	v_add_f32_e32 v44, v46, v44
	v_add_f32_e32 v46, v44, v45
	v_pk_mul_f32 v[44:45], v[10:11], v[10:11]
	s_nop 0
	v_add_f32_e32 v44, v46, v44
	v_add_f32_e32 v44, v44, v45
	ds_bpermute_b32 v45, v101, v44
	s_waitcnt lgkmcnt(0)
	v_add_f32_e32 v44, v44, v45
	ds_bpermute_b32 v45, v102, v44
	s_waitcnt lgkmcnt(0)
	v_add_f32_e32 v44, v44, v45
	ds_bpermute_b32 v45, v103, v44
	s_waitcnt lgkmcnt(0)
	v_add_f32_e32 v44, v44, v45
	v_fmamk_f32 v44, v44, 0x3b800000, v182
	v_cmp_gt_f32_e32 vcc, s56, v44
	v_mul_f32_e32 v45, 0x4b800000, v44
	s_nop 0
	v_cndmask_b32_e32 v44, v44, v45, vcc
	v_rsq_f32_e32 v44, v44
	s_nop 0
	v_mul_f32_e32 v45, 0x45800000, v44
	v_cndmask_b32_e32 v52, v44, v45, vcc
	v_mul_f32_e32 v38, v38, v52
	v_mul_f32_e32 v40, v40, v52
	v_mul_f32_e32 v36, v36, v52
	v_mul_f32_e32 v37, v37, v52
	v_mul_f32_e32 v41, v41, v52
	v_mul_f32_e32 v42, v42, v52
	v_mul_f32_e32 v43, v43, v52
	v_mul_f32_e32 v28, v28, v52
	v_mul_f32_e32 v32, v32, v52
	v_mul_f32_e32 v33, v33, v52
	v_mul_f32_e32 v34, v34, v52
	v_mul_f32_e32 v35, v35, v52
	v_mul_f32_e32 v20, v20, v52
	v_mul_f32_e32 v24, v24, v52
	v_mul_f32_e32 v8, v8, v52
	v_mul_f32_e32 v12, v12, v52
	s_waitcnt vmcnt(0)
	v_lshlrev_b32_e32 v66, 16, v56
	v_and_b32_e32 v65, 0xffff0000, v56
	v_lshlrev_b32_e32 v64, 16, v57
	v_and_b32_e32 v63, 0xffff0000, v57
	v_lshlrev_b32_e32 v57, 16, v58
	v_and_b32_e32 v56, 0xffff0000, v58
	v_and_b32_e32 v54, 0xffff0000, v59
	v_lshlrev_b32_e32 v55, 16, v59
	v_mul_f32_e32 v38, v206, v38
	v_mul_f32_e32 v40, v208, v40
	v_mul_f32_e32 v36, v204, v36
	v_mul_f32_e32 v37, v205, v37
	v_mul_f32_e32 v44, v38, v55
	v_mul_f32_e32 v38, v39, v52
	v_mul_f32_e32 v40, v40, v66
	v_mul_f32_e32 v41, v209, v41
	v_mul_f32_e32 v36, v36, v57
	v_mul_f32_e32 v37, v37, v56
	v_mul_f32_e32 v38, v207, v38
	v_mul_f32_e32 v41, v41, v65
	v_mul_f32_e32 v45, v38, v54
	v_cvt_pk_bf16_f32 v38, v40, v41
	v_cvt_pk_bf16_f32 v40, v36, v37
	v_lshl_add_u64 v[36:37], s[0:1], 0, v[60:61]
	v_mul_f32_e32 v42, v210, v42
	v_mul_f32_e32 v43, v211, v43
	v_lshl_add_u64 v[36:37], v[36:37], 0, v[156:157]
	v_mul_f32_e32 v42, v42, v64
	v_mul_f32_e32 v43, v43, v63
	v_cvt_pk_bf16_f32 v39, v42, v43
	v_cvt_pk_bf16_f32 v41, v44, v45
	global_store_dwordx4 v[36:37], v[38:41], off
	v_lshlrev_b32_e32 v42, 16, v16
	v_and_b32_e32 v43, 0xffff0000, v16
	v_lshlrev_b32_e32 v44, 16, v17
	v_and_b32_e32 v45, 0xffff0000, v17
	v_lshlrev_b32_e32 v46, 16, v18
	v_and_b32_e32 v47, 0xffff0000, v18
	v_lshlrev_b32_e32 v48, 16, v19
	v_and_b32_e32 v49, 0xffff0000, v19
	v_mul_f32_e32 v16, v28, v212
	v_mul_f32_e32 v28, v16, v46
	v_mul_f32_e32 v16, v29, v52
	v_mul_f32_e32 v16, v16, v213
	v_mul_f32_e32 v29, v16, v47
	v_mul_f32_e32 v16, v30, v52
	v_mul_f32_e32 v16, v16, v214
	v_mul_f32_e32 v30, v16, v48
	v_mul_f32_e32 v16, v31, v52
	v_mul_f32_e32 v16, v16, v215
	v_mul_f32_e32 v32, v32, v216
	v_mul_f32_e32 v33, v33, v217
	v_mul_f32_e32 v34, v34, v218
	v_mul_f32_e32 v35, v35, v219
	v_mul_f32_e32 v19, v16, v49
	v_mul_f32_e32 v32, v32, v42
	v_mul_f32_e32 v33, v33, v43
	v_mul_f32_e32 v34, v34, v44
	v_mul_f32_e32 v35, v35, v45
	v_cvt_pk_bf16_f32 v16, v32, v33
	v_cvt_pk_bf16_f32 v17, v34, v35
	v_cvt_pk_bf16_f32 v18, v28, v29
	v_cvt_pk_bf16_f32 v19, v30, v19
	global_store_dwordx4 v[36:37], v[16:19], off offset:128
	v_lshlrev_b32_e32 v28, 16, v4
	v_and_b32_e32 v29, 0xffff0000, v4
	v_lshlrev_b32_e32 v30, 16, v5
	v_and_b32_e32 v31, 0xffff0000, v5
	v_lshlrev_b32_e32 v32, 16, v6
	v_and_b32_e32 v33, 0xffff0000, v6
	v_lshlrev_b32_e32 v34, 16, v7
	v_and_b32_e32 v35, 0xffff0000, v7
	v_mul_f32_e32 v4, v20, v220
	v_mul_f32_e32 v20, v4, v32
	v_mul_f32_e32 v4, v21, v52
	v_mul_f32_e32 v4, v4, v221
	v_mul_f32_e32 v21, v4, v33
	v_mul_f32_e32 v4, v22, v52
	v_mul_f32_e32 v16, v24, v224
	v_mul_f32_e32 v24, v25, v52
	v_mul_f32_e32 v4, v4, v222
	v_mul_f32_e32 v17, v24, v225
	v_mul_f32_e32 v24, v26, v52
	v_mul_f32_e32 v22, v4, v34
	v_mul_f32_e32 v4, v23, v52
	v_mul_f32_e32 v18, v24, v226
	v_mul_f32_e32 v24, v27, v52
	v_mul_f32_e32 v4, v4, v223
	v_mul_f32_e32 v19, v24, v227
	v_mul_f32_e32 v7, v4, v35
	v_mul_f32_e32 v16, v16, v28
	v_mul_f32_e32 v17, v17, v29
	v_mul_f32_e32 v18, v18, v30
	v_mul_f32_e32 v19, v19, v31
	v_cvt_pk_bf16_f32 v4, v16, v17
	v_cvt_pk_bf16_f32 v5, v18, v19
	v_cvt_pk_bf16_f32 v6, v20, v21
	v_cvt_pk_bf16_f32 v7, v22, v7
	global_store_dwordx4 v[36:37], v[4:7], off offset:256
	v_lshlrev_b32_e32 v16, 16, v0
	v_and_b32_e32 v17, 0xffff0000, v0
	v_lshlrev_b32_e32 v18, 16, v1
	v_and_b32_e32 v19, 0xffff0000, v1
	v_lshlrev_b32_e32 v20, 16, v2
	v_and_b32_e32 v21, 0xffff0000, v2
	v_lshlrev_b32_e32 v22, 16, v3
	v_and_b32_e32 v23, 0xffff0000, v3
	v_mul_f32_e32 v0, v8, v228
	v_mul_f32_e32 v8, v0, v20
	v_mul_f32_e32 v0, v9, v52
	v_mul_f32_e32 v0, v0, v229
	v_mul_f32_e32 v9, v0, v21
	v_mul_f32_e32 v0, v10, v52
	v_mul_f32_e32 v4, v12, v232
	v_mul_f32_e32 v12, v13, v52
	v_mul_f32_e32 v0, v0, v230
	v_mul_f32_e32 v5, v12, v233
	v_mul_f32_e32 v12, v14, v52
	v_mul_f32_e32 v10, v0, v22
	v_mul_f32_e32 v0, v11, v52
	v_mul_f32_e32 v6, v12, v234
	v_mul_f32_e32 v12, v15, v52
	v_mul_f32_e32 v0, v0, v231
	v_mul_f32_e32 v7, v12, v235
	v_mul_f32_e32 v3, v0, v23
	v_mul_f32_e32 v4, v4, v16
	v_mul_f32_e32 v5, v5, v17
	v_mul_f32_e32 v6, v6, v18
	v_mul_f32_e32 v7, v7, v19
	v_cvt_pk_bf16_f32 v0, v4, v5
	v_cvt_pk_bf16_f32 v1, v6, v7
	v_cvt_pk_bf16_f32 v2, v8, v9
	v_cvt_pk_bf16_f32 v3, v10, v3
	global_store_dwordx4 v[36:37], v[0:3], off offset:384
	s_barrier
